# attention main path: softmax tail (row-sum adds, bf16 packing) and tile-address increments woven into the PV MFMA gaps, temps renamed to v240-250
# baseline (speedup 1.0000x reference)
; DI void attn_unit(Ctx A_, LAS unsigned char* lds, int b, int h, int qb, float lam, int wave, int lane) {
;     ...
; #pragma unroll 1
;     for (int t = 0; t <= NT; ++t) {
;         asm volatile("s_waitcnt vmcnt(0) lgkmcnt(0)" ::: "memory");
;         __builtin_amdgcn_s_barrier(); asm volatile("" ::: "memory");
;         if (t + 2 < NT) load_tile(lds + ((t + 2) & 3) * BUF, Kg, Vg, (t + 2) * 64, wave, lane);
.LBB0_871:
	s_add_i32 s67, s67, 1
	s_add_i32 s66, s66, 0x8000
	s_cmp_eq_u32 s14, s66
	s_cbranch_scc1 .LBB0_890

; #define LAS __attribute__((address_space(3)))
; DI int crow(int i, int hh) { return (i & 3) + 8 * (i >> 2) + 4 * hh; }
; #define LOADV(f, ks) _Pragma("unroll") for (int nb = 0; nb < 4; ++nb) { const s16x4 lo = vtr(vp + nb * 4096 + (ks) * 1024), hi = vtr(vp + nb * 4096 + (ks) * 1024 + 512); f[nb] = __builtin_shufflevector(lo, hi, 0, 1, 2, 3, 4, 5, 6, 7); }
; #define SB __builtin_amdgcn_sched_barrier(0);
; DI void attn_unit(Ctx A_, LAS unsigned char* lds, int b, int h, int qb, float lam, int wave, int lane) {
;     ...
;             bf16x8 pfn[4]; float ls = 0.f;
;             {
;               float qa_ = 0.f, qb_ = 0.f;
;     ...
;               SB __builtin_amdgcn_s_setprio(1); SB
;               GRP(p0, 0, fa4, 0, 0) GRP(p0, 2, fa4, 0, 1) GRP(p0, 4, fa4, 0, 2) GRP(p0, 6, fa4, 0, 3)
;               LOADV(fa4, 2) SB
;               pfn[0] = pack8(p0, 0);
;               GRP(p0, 8, fb4, 1, 0) GRP(p0, 10, fb4, 1, 1) GRP(p0, 12, fb4, 1, 2) GRP(p0, 14, fb4, 1, 3)
;               LOADV(fb4, 3) SB
;               { const LAS unsigned char* kn = lds + ((t + 1) & 3) * BUF + (mp * 8 + hh) * 1024 + r * 16;
; #pragma unroll
;                 for (int d0 = 0; d0 < 2; ++d0) { kfa[2 * d0] = *(const LAS bf16x8*)(kn + d0 * 2048); kfa[2 * d0 + 1] = *(const LAS bf16x8*)(kn + d0 * 2048 + 512); } }
;               SB
;               pfn[1] = pack8(p0, 8);
;               GRP(p1, 0, fa4, 2, 0) GRP(p1, 2, fa4, 2, 1) GRP(p1, 4, fa4, 2, 2) GRP(p1, 6, fa4, 2, 3)
;               pfn[2] = pack8(p1, 0);
;               GRP(p1, 8, fb4, 3, 0) GRP(p1, 10, fb4, 3, 1) GRP(p1, 12, fb4, 3, 2) GRP(p1, 14, fb4, 3, 3)
;               __builtin_amdgcn_s_setprio(0); SB
;               ls += qa_ + qb_; pfn[3] = pack8(p1, 8);
;     ...
;             }
;             l += ls;
; #pragma unroll
;             for (int i = 0; i < 4; ++i) pfc[i] = pfn[i];
;             if (resc) {
;                 float fr[16];
; #pragma unroll
;                 for (int i = 0; i < 16; ++i) fr[i] = wsf[crow(i, hh)];
; #pragma unroll
;                 for (int nb = 0; nb < 4; ++nb)
; #pragma unroll
;                     for (int i = 0; i < 16; ++i) o[nb][i] *= fr[i];
;             }
.LBB0_886:
	s_setprio 1
	v_mfma_f32_32x32x16_bf16 v[34:49], v[190:193], v[134:137], v[34:49]
	v_exp_f32 v221, v98
	v_exp_f32 v222, v99
	v_lshl_add_u64 v[198:199], v[198:199], 0, s[18:19]
	s_waitcnt lgkmcnt(10)
	v_mfma_f32_32x32x16_bf16 v[50:65], v[190:193], v[142:145], v[50:65]
	v_exp_f32 v134, v100
	v_exp_f32 v135, v101
	v_add_f32_e32 v240, v221, v222
	v_lshl_add_u64 v[200:201], v[200:201], 0, s[18:19]
	s_waitcnt lgkmcnt(6)
	v_mfma_f32_32x32x16_bf16 v[18:33], v[190:193], v[138:141], v[18:33]
	v_exp_f32 v136, v102
	v_exp_f32 v137, v103
	v_add_f32_e32 v241, v134, v135
	v_add_f32_e32 v240, 0, v240
	s_waitcnt lgkmcnt(2)
	v_mfma_f32_32x32x16_bf16 v[2:17], v[190:193], v[130:133], v[2:17]
	v_exp_f32 v138, v104
	v_exp_f32 v139, v105
	v_add_f32_e32 v242, v136, v137
	v_add_f32_e32 v243, v240, v241
	ds_read_b64_tr_b16 v[130:131], v220 offset:18432
	ds_read_b64_tr_b16 v[132:133], v220 offset:18944
	ds_read_b64_tr_b16 v[140:141], v220 offset:22528
	ds_read_b64_tr_b16 v[142:143], v220 offset:23040
	ds_read_b64_tr_b16 v[190:191], v220 offset:26624
	ds_read_b64_tr_b16 v[192:193], v220 offset:27136
	ds_read_b64_tr_b16 v[224:225], v220 offset:30720
	ds_read_b64_tr_b16 v[226:227], v220 offset:31232
	v_mfma_f32_32x32x16_bf16 v[34:49], v[170:173], v[126:129], v[34:49]
	v_exp_f32 v100, v106
	v_exp_f32 v98, v107
	v_add_f32_e32 v244, v138, v139
	v_add_f32_e32 v242, v243, v242
	v_mfma_f32_32x32x16_bf16 v[50:65], v[170:173], v[122:125], v[50:65]
	v_exp_f32 v101, v108
	v_exp_f32 v99, v109
	v_add_f32_e32 v242, v242, v244
	v_lshl_add_u64 v[202:203], v[202:203], 0, s[18:19]
	v_mfma_f32_32x32x16_bf16 v[18:33], v[170:173], v[118:121], v[18:33]
	v_exp_f32 v104, v110
	v_exp_f32 v102, v111
	v_pk_add_f32 v[240:241], v[100:101], v[98:99]
	v_add_f32_e32 v240, v242, v240
	s_waitcnt lgkmcnt(8)
	v_mfma_f32_32x32x16_bf16 v[2:17], v[170:173], v[114:117], v[2:17]
	v_exp_f32 v105, v112
	v_exp_f32 v103, v113
	v_add_f32_e32 v242, v240, v241
	v_cvt_pk_bf16_f32 v170, v100, v98
	v_cvt_pk_bf16_f32 v171, v101, v99
	ds_read_b64_tr_b16 v[114:115], v220 offset:19456
	ds_read_b64_tr_b16 v[116:117], v220 offset:19968
	ds_read_b64_tr_b16 v[118:119], v220 offset:23552
	ds_read_b64_tr_b16 v[120:121], v220 offset:24064
	ds_read_b64_tr_b16 v[122:123], v220 offset:27648
	ds_read_b64_tr_b16 v[124:125], v220 offset:28160
	ds_read_b64_tr_b16 v[126:127], v220 offset:31744
	ds_read_b64_tr_b16 v[128:129], v220 offset:32256
	s_add_i32 s4, s66, 0x8000
	s_and_b32 s4, s4, 0x18000
	v_add_u32_e32 v106, s4, v216
	ds_read_b128 v[174:177], v106
	ds_read_b128 v[178:181], v106 offset:512
	ds_read_b128 v[182:185], v106 offset:2048
	ds_read_b128 v[186:189], v106 offset:2560
	s_waitcnt lgkmcnt(14)
	v_mfma_f32_32x32x16_bf16 v[34:49], v[166:169], v[130:133], v[34:49]
	v_exp_f32 v108, v82
	v_exp_f32 v106, v83
	v_pk_add_f32 v[240:241], v[104:105], v[102:103]
	v_add_f32_e32 v240, v242, v240
	v_cvt_pk_bf16_f32 v172, v104, v102
	v_mfma_f32_32x32x16_bf16 v[50:65], v[166:169], v[140:143], v[50:65]
	v_exp_f32 v109, v84
	v_exp_f32 v107, v85
	v_add_f32_e32 v250, v240, v241
	v_cvt_pk_bf16_f32 v173, v105, v103
	v_mfma_f32_32x32x16_bf16 v[18:33], v[166:169], v[190:193], v[18:33]
	v_exp_f32 v112, v86
	v_exp_f32 v110, v87
	v_pk_add_f32 v[242:243], v[108:109], v[106:107]
	v_cvt_pk_bf16_f32 v190, v221, v222
	s_waitcnt lgkmcnt(12)
	v_mfma_f32_32x32x16_bf16 v[2:17], v[166:169], v[224:227], v[2:17]
	v_exp_f32 v113, v88
	v_exp_f32 v111, v89
	v_add_f32_e32 v250, v250, v242
	v_cvt_pk_bf16_f32 v191, v134, v135
	v_cvt_pk_bf16_f32 v166, v108, v106
	s_waitcnt lgkmcnt(10)
	v_mfma_f32_32x32x16_bf16 v[34:49], v[162:165], v[114:117], v[34:49]
	v_exp_f32 v84, v90
	v_exp_f32 v82, v91
	v_pk_add_f32 v[244:245], v[112:113], v[110:111]
	v_add_f32_e32 v250, v250, v243
	v_cvt_pk_bf16_f32 v192, v136, v137
	s_waitcnt lgkmcnt(8)
	v_mfma_f32_32x32x16_bf16 v[50:65], v[162:165], v[118:121], v[50:65]
	v_exp_f32 v85, v92
	v_exp_f32 v83, v93
	v_add_f32_e32 v250, v250, v244
	v_add_f32_e32 v250, v250, v245
	v_cvt_pk_bf16_f32 v193, v138, v139
	s_waitcnt lgkmcnt(6)
	v_mfma_f32_32x32x16_bf16 v[18:33], v[162:165], v[122:125], v[18:33]
	v_exp_f32 v88, v94
	v_exp_f32 v86, v95
	v_pk_add_f32 v[246:247], v[84:85], v[82:83]
	v_cvt_pk_bf16_f32 v167, v109, v107
	v_cvt_pk_bf16_f32 v168, v112, v110
	s_waitcnt lgkmcnt(4)
	v_mfma_f32_32x32x16_bf16 v[2:17], v[162:165], v[126:129], v[2:17]
	v_exp_f32 v89, v96
	v_exp_f32 v87, v97
	v_add_f32_e32 v250, v250, v246
	v_cvt_pk_bf16_f32 v169, v113, v111
	v_cvt_pk_bf16_f32 v162, v84, v82
	v_cvt_pk_bf16_f32 v163, v85, v83
	s_setprio 0
	s_and_b64 vcc, exec, s[6:7]
	s_cbranch_vccnz .LBB0_888
	v_add_u32_e32 v118, s40, v194
	ds_read_b128 v[90:93], v118 offset:96
	ds_read_b128 v[94:97], v118 offset:64
	ds_read_b128 v[114:117], v118 offset:32
	ds_read_b128 v[118:121], v118
	s_waitcnt lgkmcnt(3)
	v_pk_mul_f32 v[46:47], v[46:47], v[90:91]
	s_waitcnt lgkmcnt(2)
	v_pk_mul_f32 v[42:43], v[42:43], v[94:95]
	s_waitcnt lgkmcnt(1)
	v_pk_mul_f32 v[38:39], v[38:39], v[114:115]
	v_pk_mul_f32 v[48:49], v[48:49], v[92:93]
	v_pk_mul_f32 v[44:45], v[44:45], v[96:97]
	v_pk_mul_f32 v[40:41], v[40:41], v[116:117]
	s_waitcnt lgkmcnt(0)
	v_pk_mul_f32 v[36:37], v[36:37], v[120:121]
	v_pk_mul_f32 v[34:35], v[34:35], v[118:119]
	v_pk_mul_f32 v[62:63], v[62:63], v[90:91]
	v_pk_mul_f32 v[58:59], v[58:59], v[94:95]
	v_pk_mul_f32 v[54:55], v[54:55], v[114:115]
	v_pk_mul_f32 v[64:65], v[64:65], v[92:93]
	v_pk_mul_f32 v[60:61], v[60:61], v[96:97]
	v_pk_mul_f32 v[56:57], v[56:57], v[116:117]
	v_pk_mul_f32 v[52:53], v[52:53], v[120:121]
	v_pk_mul_f32 v[50:51], v[50:51], v[118:119]
	v_pk_mul_f32 v[30:31], v[30:31], v[90:91]
	v_pk_mul_f32 v[26:27], v[26:27], v[94:95]
	v_pk_mul_f32 v[22:23], v[22:23], v[114:115]
	v_pk_mul_f32 v[32:33], v[32:33], v[92:93]
	v_pk_mul_f32 v[28:29], v[28:29], v[96:97]
	v_pk_mul_f32 v[24:25], v[24:25], v[116:117]
	v_pk_mul_f32 v[20:21], v[20:21], v[120:121]
	v_pk_mul_f32 v[18:19], v[18:19], v[118:119]
	v_pk_mul_f32 v[14:15], v[14:15], v[90:91]
	v_pk_mul_f32 v[10:11], v[10:11], v[94:95]
	v_pk_mul_f32 v[6:7], v[6:7], v[114:115]
	v_pk_mul_f32 v[16:17], v[16:17], v[92:93]
	v_pk_mul_f32 v[12:13], v[12:13], v[96:97]
	v_pk_mul_f32 v[8:9], v[8:9], v[116:117]
	v_pk_mul_f32 v[4:5], v[4:5], v[120:121]
	v_pk_mul_f32 v[2:3], v[2:3], v[118:119]
.LBB0_888:
	v_add_f32_e32 v250, v250, v247
	v_pk_add_f32 v[248:249], v[88:89], v[86:87]
	v_cvt_pk_bf16_f32 v164, v88, v86
	v_cvt_pk_bf16_f32 v165, v89, v87
	v_add_f32_e32 v250, v250, v248
	v_add_f32_e32 v250, v250, v249
	v_add_f32_e32 v218, v218, v250
	s_branch .LBB0_871
